# XCD-local barrier between FFN1-FFN2 and gate-branch phases when workgroup placement is round-robin
# baseline (speedup 1.0000x reference)
; #define LAS __attribute__((address_space(3)))
; __device__ __forceinline__ unsigned xb_add(unsigned* p, unsigned v) { return __hip_atomic_fetch_add(p, v, __ATOMIC_RELAXED, __HIP_MEMORY_SCOPE_AGENT); }
; __device__ __forceinline__ unsigned xb_xcc_id() { return (unsigned)__builtin_amdgcn_s_getreg((3 << 11) | 20) & 0xFu; }
; __device__ __forceinline__ XcdBarrier xcd_barrier_post(unsigned* bar, volatile LAS unsigned* st) {
;     XcdBarrier b; b.bar = bar; b.x = xb_xcc_id(); b.st = st;
;     if (threadIdx.x == 0) (void)xb_add(&bar[XB_XCNT(b.x)], 1u);
;     return b;
; __global__ void __launch_bounds__(NTHR) mega_fwd(Args a) {
;     ...
;     const float* NG_ = a.in[I_NORMG];
;     volatile LAS unsigned* xst = (volatile LAS unsigned*)(lds + LDS_BYTES - 16);
;     if (threadIdx.x == 0) { xst[0] = 0u; xst[1] = 0u; xst[2] = 0u; xst[3] = 0u; }
;     __syncthreads();
;     XcdBarrier xbar = xcd_barrier_post((unsigned*)(ws + WS_BAR), xst);
;     for (int rep = 0; rep < REP_PRO; ++rep) {
;     convert_weights(a, 0, lds);
.LBB0_2:
	s_or_b64 exec, exec, s[2:3]
	s_load_dwordx16 s[4:19], s[0:1], 0x0
	s_load_dwordx16 s[76:91], s[0:1], 0x40
	s_waitcnt lgkmcnt(0)
	s_barrier
	v_writelane_b32 v249, s4, 12
	s_add_u32 s2, s72, 0x1d1d1000
	s_getreg_b32 s0, hwreg(HW_REG_XCC_ID, 0, 4)
	v_writelane_b32 v249, s5, 13
	v_writelane_b32 v249, s6, 14
	v_writelane_b32 v249, s7, 15
	v_writelane_b32 v249, s8, 16
	v_writelane_b32 v249, s9, 17
	v_writelane_b32 v249, s10, 18
	v_writelane_b32 v249, s11, 19
	v_writelane_b32 v249, s12, 20
	v_writelane_b32 v249, s13, 21
	v_writelane_b32 v249, s14, 22
	v_writelane_b32 v249, s15, 23
	v_writelane_b32 v249, s16, 24
	v_writelane_b32 v249, s17, 25
	v_writelane_b32 v249, s18, 26
	s_addc_u32 s3, s73, 0
	s_and_b32 s26, s0, 15
	v_writelane_b32 v249, s19, 27
	s_lshl_b32 s25, s26, 6
	s_mov_b64 s[0:1], exec
	v_readlane_b32 s4, v249, 10
	v_readlane_b32 s5, v249, 11
	s_and_b64 s[4:5], s[0:1], s[4:5]
	s_mov_b64 exec, s[4:5]
	s_cbranch_execz .LBB0_5
	s_mov_b64 s[4:5], exec
	v_mbcnt_lo_u32_b32 v1, s4, 0
	v_mbcnt_hi_u32_b32 v1, s5, v1
	v_cmp_eq_u32_e32 vcc, 0, v1
	s_and_b64 s[6:7], exec, vcc
	s_mov_b64 exec, s[6:7]
	s_cbranch_execz .LBB0_5
	s_lshl_b32 s6, s25, 2
	s_bcnt1_i32_b64 s4, s[4:5]
	v_mov_b32_e32 v1, s6
	v_mov_b32_e32 v2, s4
	global_atomic_add v1, v2, s[2:3] offset:1024
	s_and_b32 s4, s41, 7
	s_cmp_lg_u32 s4, s26
	s_cselect_b32 s4, 1, 0
	s_cmpk_lg_u32 s74, 0x100
	s_cselect_b32 s5, 1, 0
	s_or_b32 s4, s4, s5
	s_cmp_eq_u32 s4, 0
	s_cbranch_scc1 .Lplace_ok
	v_mov_b32_e32 v5, 0
	v_mov_b32_e32 v6, 1
	global_atomic_add v5, v6, s[2:3] offset:480
.Lplace_ok:
.LBB0_5:
	s_or_b64 exec, exec, s[0:1]
	s_cmpk_lt_i32 s41, 0xd40
	s_cselect_b64 s[0:1], -1, 0
	s_add_u32 s4, s72, 0xb00000
	s_addc_u32 s5, s73, 0
	v_writelane_b32 v249, s4, 28
	v_mov_b32_e32 v1, v199
	s_nop 0
	v_writelane_b32 v249, s5, 29
	s_add_u32 s4, s72, 0x1600000
	s_addc_u32 s5, s73, 0
	v_writelane_b32 v249, s4, 30
	v_ashrrev_i32_e32 v2, 3, v1
	s_nop 0
	v_writelane_b32 v249, s5, 31
	s_add_u32 s4, s72, 0x1b80000
	s_addc_u32 s5, s73, 0
	v_writelane_b32 v249, s4, 32
	s_nop 1
	v_writelane_b32 v249, s5, 33
	s_add_u32 s4, s72, 0x2100000
	s_addc_u32 s5, s73, 0
	v_writelane_b32 v249, s4, 34
	s_nop 1
	v_writelane_b32 v249, s5, 35
	s_add_u32 s4, s72, 0x2900000
	s_addc_u32 s5, s73, 0
	v_writelane_b32 v249, s4, 36
	s_nop 1
	v_writelane_b32 v249, s5, 37
	s_add_u32 s4, s72, 0x2f00000
	s_addc_u32 s5, s73, 0
	v_writelane_b32 v249, s4, 38
	s_nop 1
	v_writelane_b32 v249, s5, 39
	s_add_u32 s4, s72, 0x3000000
	s_addc_u32 s5, s73, 0
	v_writelane_b32 v249, s4, 40
	s_nop 1
	v_writelane_b32 v249, s5, 41
	s_add_u32 s4, s72, 0x3100000
	s_addc_u32 s5, s73, 0
	v_writelane_b32 v249, s4, 42
	s_nop 1
	v_writelane_b32 v249, s5, 43
	s_add_u32 s4, s72, 0x3200000
	s_addc_u32 s5, s73, 0
	v_writelane_b32 v249, s4, 44
	s_nop 1
	v_writelane_b32 v249, s5, 45
	s_add_u32 s4, s72, 0x3800000
	s_addc_u32 s5, s73, 0
	v_writelane_b32 v249, s4, 46
	s_nop 1
	v_writelane_b32 v249, s5, 47
	s_add_u32 s4, s72, 0x3840000
	s_addc_u32 s5, s73, 0
	v_writelane_b32 v249, s4, 48
	s_nop 1
	v_writelane_b32 v249, s5, 49
	s_add_u32 s4, s72, 0x3880000
	s_addc_u32 s5, s73, 0
	v_writelane_b32 v249, s4, 50
	s_nop 1
	v_writelane_b32 v249, s5, 51
	s_add_u32 s4, s72, 0x38c0000
	s_addc_u32 s5, s73, 0
	v_writelane_b32 v249, s4, 52
	s_nop 1
	v_writelane_b32 v249, s5, 53
	v_writelane_b32 v249, s0, 54
	s_and_b64 vcc, exec, s[0:1]
	s_nop 0
	v_writelane_b32 v249, s1, 55
	s_cbranch_vccz .LBB0_95
	v_readlane_b32 s4, v249, 12
	v_readlane_b32 s14, v249, 22
	v_readlane_b32 s15, v249, 23
	s_add_u32 s0, s14, 0x1600000
	v_readlane_b32 s16, v249, 24
	s_addc_u32 s1, s15, 0
	v_readlane_b32 s5, v249, 13
	v_readlane_b32 s8, v249, 16
	v_readlane_b32 s9, v249, 17
	v_readlane_b32 s10, v249, 18
	v_readlane_b32 s11, v249, 19
	v_readlane_b32 s12, v249, 20
	v_readlane_b32 s13, v249, 21
	v_readlane_b32 s17, v249, 25
	s_add_u32 s4, s16, 0xb00000
	v_readlane_b32 s6, v249, 14
	s_addc_u32 s5, s17, 0
	v_readlane_b32 s8, v249, 0
	v_readlane_b32 s7, v249, 15
	v_readlane_b32 s9, v249, 1
	s_add_u32 s6, s8, 0x200000
	s_addc_u32 s7, s9, 0
	s_add_u32 s8, s8, 0x400000
	v_readlane_b32 s10, v249, 2
	s_addc_u32 s9, s9, 0
	v_readlane_b32 s11, v249, 3
	s_add_u32 s10, s86, 0x80000
	v_readlane_b32 s12, v249, 4
	s_addc_u32 s11, s87, 0
	v_lshlrev_b32_e32 v4, 3, v1
	v_readlane_b32 s13, v249, 5
	s_add_u32 s12, s86, 0x100000
	v_and_b32_e32 v4, 56, v4
	v_readlane_b32 s14, v249, 6
	s_addc_u32 s13, s87, 0
	v_and_b32_e32 v3, 63, v1
	v_ashrrev_i32_e32 v10, 6, v1
	s_movk_i32 s16, 0x104
	v_mul_u32_u24_e32 v5, 0x104, v4
	v_lshlrev_b32_e32 v8, 2, v2
	v_readlane_b32 s15, v249, 7
	s_add_u32 s14, s86, 0x180000
	v_lshl_add_u32 v6, v3, 2, 0
	v_mul_lo_u32 v7, v10, s16
	v_add3_u32 v11, 0, v5, v8
	s_addc_u32 s15, s87, 0
	v_mov_b32_e32 v5, 0
	v_add_u32_e32 v12, 0x4100, v11
	v_add_u32_e32 v13, v6, v7
	v_lshlrev_b32_e32 v6, 1, v4
	s_mov_b32 s27, s41
	v_readlane_b32 s18, v249, 26
	v_readlane_b32 s19, v249, 27
	s_branch .LBB0_8

; __device__ __forceinline__ int opaque_tid() { int t = (int)threadIdx.x; asm volatile("" : "+v"(t)); return t; }
; __device__ __forceinline__ void norm_phase(const void* xin, bool xin_bf, const bf16_t* y, const float* gpost, const float* mgate, float rw,
;                                            const float* gpre, const float* mshift, const float* mscale, void* xout, bool xout_bf, bf16_t* h) {
;     const int otid = opaque_tid();
;     const int lane = otid & 63, w = otid >> 6;
;     const int nw = gridDim.x * 8, rows_per = NTOK / nw;
;     const int gw = blockIdx.x * 8 + w;
;     const int r0 = gw * rows_per, b = r0 / SQ;
.LBB0_184:
	s_or_b64 exec, exec, s[0:1]
	s_add_u32 s92, s72, 0x3a00000
	s_addc_u32 s93, s73, 0
	s_lshl_b32 s0, s74, 3
	v_writelane_b32 v251, s0, 13
	s_abs_i32 s0, s0
	s_waitcnt lgkmcnt(0)
	v_cvt_f32_u32_e32 v0, s0
	s_sub_i32 s2, 0, s0
	s_bfe_i32 s1, s74, 0x1001c
	v_readlane_b32 s26, v250, 7
	v_rcp_iflag_f32_e32 v0, v0
	v_mov_b32_e32 v8, v199
	v_mbcnt_lo_u32_b32 v109, -1, 0
	v_readlane_b32 s27, v250, 8
	v_mul_f32_e32 v0, 0x4f7ffffe, v0
	v_cvt_u32_f32_e32 v0, v0
	s_barrier
	v_readlane_b32 s4, v249, 10
	v_readlane_b32 s5, v249, 11
	s_mov_b64 s[6:7], exec
	s_and_b64 s[4:5], s[6:7], s[4:5]
	s_mov_b64 exec, s[4:5]
	s_cbranch_execz .Ldec_skip
	v_readlane_b32 s4, v251, 9
	v_readlane_b32 s5, v251, 10
	s_sub_u32 s4, s4, 0x3220
	s_subb_u32 s5, s5, 0
	v_mov_b32_e32 v5, 0
	global_load_dword v6, v5, s[4:5] sc1
	s_and_b32 s8, s41, 7
	s_lshl_b32 s8, s8, 6
	s_add_u32 s8, s8, 1
	s_waitcnt vmcnt(0)
	v_cmp_eq_u32_e32 vcc, 0, v6
	v_mov_b32_e32 v7, s8
	v_cndmask_b32_e32 v7, 0, v7, vcc
	v_mov_b32_e32 v5, 0x23ffc
	ds_write_b32 v5, v7
	s_waitcnt lgkmcnt(0)
; __device__ __forceinline__ int opaque_tid() { int t = (int)threadIdx.x; asm volatile("" : "+v"(t)); return t; }
; __device__ __forceinline__ void norm_load(NormRows& R, const void* xin, bool xin_bf, const bf16_t* y, int r, int lane) {
; #pragma unroll
;     for (int q = 0; q < 2; ++q)
; #pragma unroll
;         for (int s = 0; s < 4; ++s) {
;             const size_t e = (size_t)(r + q) * DM + s * 256 + lane * 4;
;             if (xin_bf) { const u32x2 t = __builtin_nontemporal_load((const u32x2*)((const bf16_t*)xin + e));
;                 R.xv[q][s] = (f32x4){__uint_as_float(t.x << 16), __uint_as_float(t.x & 0xffff0000u), __uint_as_float(t.y << 16), __uint_as_float(t.y & 0xffff0000u)}; }
;             else R.xv[q][s] = __builtin_nontemporal_load((const f32x4*)((const float*)xin + e));
; __device__ __forceinline__ void norm_phase(const void* xin, bool xin_bf, const bf16_t* y, const float* gpost, const float* mgate, float rw,
;                                            const float* gpre, const float* mshift, const float* mscale, void* xout, bool xout_bf, bf16_t* h) {
;     const int otid = opaque_tid();
;     const int lane = otid & 63, w = otid >> 6;
;     const int nw = gridDim.x * 8, rows_per = NTOK / nw;
;     const int gw = blockIdx.x * 8 + w;
;     const int r0 = gw * rows_per, b = r0 / SQ;
;     f32x4 gp[4], pa[4];
; #pragma unroll
;     for (int s = 0; s < 4; ++s) {
;         const int c = s * 256 + lane * 4;
;         if (y) { const f32x4 g1 = *(const f32x4*)(mgate + b * 9216 + c), g2 = *(const f32x4*)(gpost + c); gp[s] = g1 * g2 * rw; } else gp[s] = (f32x4){0.f, 0.f, 0.f, 0.f};
;         if (h) { const f32x4 g1 = *(const f32x4*)(gpre + c), g2 = *(const f32x4*)(mscale + b * 9216 + c); pa[s] = g1 * (g2 + 1.f); }
;         else { pa[s] = (f32x4){0.f, 0.f, 0.f, 0.f}; }
;     }
;     NormRows A, B;
;     norm_load(A, xin, xin_bf, y, r0, lane);
.Ldec_skip:
	s_mov_b64 exec, s[6:7]
	v_readfirstlane_b32 s3, v0
	s_mul_i32 s2, s2, s3
	s_mul_hi_u32 s2, s3, s2
	s_add_i32 s3, s3, s2
	s_lshr_b32 s2, s3, 17
	s_mul_i32 s3, s2, s0
	s_sub_i32 s3, 0x8000, s3
	s_add_i32 s4, s2, 1
	s_sub_i32 s5, s3, s0
	s_cmp_ge_u32 s3, s0
	s_cselect_b32 s2, s4, s2
	s_cselect_b32 s3, s5, s3
	s_add_i32 s4, s2, 1
	s_cmp_ge_u32 s3, s0
	s_cselect_b32 s0, s4, s2
	s_xor_b32 s0, s0, s1
	s_sub_i32 s0, s0, s1
	s_lshl_b32 s1, s41, 3
	v_writelane_b32 v249, s1, 56
	s_cmp_gt_i32 s0, 0
	v_writelane_b32 v249, s0, 57
	s_cselect_b64 s[0:1], -1, 0
	v_writelane_b32 v251, s0, 14
	s_and_b64 vcc, exec, s[0:1]
	s_nop 0
	v_writelane_b32 v251, s1, 15
	s_cbranch_vccz .LBB0_190
	v_ashrrev_i32_e32 v0, 6, v8
	v_readlane_b32 s0, v249, 56
	v_readlane_b32 s3, v249, 57
	v_lshlrev_b32_e32 v1, 2, v8
	v_add_u32_e32 v0, s0, v0
	v_mul_lo_u32 v4, v0, s3
	v_ashrrev_i32_e32 v5, 31, v4
	v_lshrrev_b32_e32 v0, 20, v5
	v_add_u32_e32 v0, v4, v0
	v_ashrrev_i32_e32 v0, 12, v0
	v_mul_i32_i24_e32 v0, 0x2400, v0
	v_and_b32_e32 v38, 0xfc, v1
	v_ashrrev_i32_e32 v1, 31, v0
	v_lshlrev_b64 v[6:7], 2, v[0:1]
	v_lshl_add_u64 v[0:1], s[72:73], 0, v[6:7]
	v_lshlrev_b32_e32 v68, 2, v38
	v_mov_b32_e32 v69, 0
	v_lshl_add_u64 v[10:11], v[0:1], 0, v[68:69]
	s_mov_b32 s2, 0x1d101000
	v_add_co_u32_e32 v0, vcc, s2, v10
	s_mov_b64 s[0:1], 0x1d101000
	s_nop 0
	v_addc_co_u32_e32 v1, vcc, 0, v11, vcc
	global_load_dwordx4 v[0:3], v[0:1], off
	v_readlane_b32 s4, v249, 12
	v_lshl_add_u64 v[18:19], v[10:11], 0, s[0:1]
	v_readlane_b32 s12, v249, 20
	v_readlane_b32 s13, v249, 21
	global_load_dwordx4 v[10:13], v[18:19], off offset:1024
	global_load_dwordx4 v[14:17], v[18:19], off offset:2048
	s_nop 0
	global_load_dwordx4 v[18:21], v[18:19], off offset:3072
	s_nop 0
	global_load_dwordx4 v[22:25], v68, s[12:13]
	global_load_dwordx4 v[26:29], v68, s[12:13] offset:1024
	global_load_dwordx4 v[30:33], v68, s[12:13] offset:2048
	global_load_dwordx4 v[34:37], v68, s[12:13] offset:3072
	v_mbcnt_hi_u32_b32 v40, -1, v109
	v_and_b32_e32 v39, 64, v40
	v_xor_b32_e32 v41, 32, v40
	v_add_u32_e32 v48, 64, v39
	v_xor_b32_e32 v43, 16, v40
	v_cmp_lt_i32_e32 vcc, v41, v48
	v_xor_b32_e32 v44, 8, v40
	v_readlane_b32 s5, v249, 13
	v_cndmask_b32_e32 v41, v40, v41, vcc
	v_cmp_lt_i32_e32 vcc, v43, v48
	v_xor_b32_e32 v45, 4, v40
	v_xor_b32_e32 v46, 2, v40
	v_cndmask_b32_e32 v43, v40, v43, vcc
	v_cmp_lt_i32_e32 vcc, v44, v48
	v_readlane_b32 s6, v249, 14
	v_readlane_b32 s7, v249, 15
	v_cndmask_b32_e32 v44, v40, v44, vcc
	v_cmp_lt_i32_e32 vcc, v45, v48
	v_and_b32_e32 v42, 63, v8
	v_mov_b32_e32 v9, v69
	v_xor_b32_e32 v47, 1, v40
	v_lshlrev_b32_e32 v8, 1, v38
	v_cndmask_b32_e32 v45, v40, v45, vcc
	v_cmp_lt_i32_e32 vcc, v46, v48
	v_readlane_b32 s6, v249, 58
	v_lshl_add_u64 v[70:71], s[92:93], 0, v[8:9]
	v_cndmask_b32_e32 v46, v40, v46, vcc
	v_cmp_lt_i32_e32 vcc, v47, v48
	v_lshlrev_b64 v[8:9], 12, v[4:5]
	v_readlane_b32 s7, v249, 59
	v_cndmask_b32_e32 v40, v40, v47, vcc
	v_lshl_add_u64 v[8:9], s[4:5], 0, v[8:9]
	s_movk_i32 s2, 0x1000
	v_lshl_add_u64 v[38:39], s[6:7], 0, v[68:69]
	v_lshlrev_b32_e32 v111, 2, v41
	v_lshlrev_b32_e32 v116, 2, v40
	v_lshl_add_u64 v[40:41], v[8:9], 0, v[68:69]
	s_mov_b64 s[0:1], 0x1000
	v_lshl_add_u64 v[76:77], v[38:39], 0, v[6:7]
	v_add_u32_e32 v110, s3, v4
	v_add_u32_e32 v74, 5, v4
	v_lshl_add_u64 v[8:9], v[40:41], 0, s[0:1]
	v_readlane_b32 s10, v249, 18
	v_lshl_add_u64 v[72:73], s[4:5], 0, v[68:69]
	v_lshlrev_b32_e32 v112, 2, v43
	v_lshlrev_b32_e32 v113, 2, v44
	v_lshlrev_b32_e32 v114, 2, v45
	v_lshlrev_b32_e32 v115, 2, v46
	v_lshlrev_b32_e32 v68, 4, v42
	v_lshlrev_b32_e32 v96, 3, v42
	v_mov_b32_e32 v97, v69
	s_mov_b64 s[0:1], 0
	s_mov_b32 s3, 0x800000
	s_mov_b32 s10, 0x3a00000
	s_mov_b64 s[6:7], 0x2000
	v_mov_b32_e32 v108, 0x358637bd
	v_readlane_b32 s8, v249, 16
	v_readlane_b32 s9, v249, 17
	v_readlane_b32 s11, v249, 19
	v_readlane_b32 s14, v249, 22
	v_readlane_b32 s15, v249, 23
	v_readlane_b32 s16, v249, 24
	v_readlane_b32 s17, v249, 25
	v_readlane_b32 s18, v249, 26
	v_readlane_b32 s19, v249, 27
	s_waitcnt vmcnt(7)
	v_pk_add_f32 v[0:1], v[0:1], 1.0 op_sel_hi:[1,0]
	v_pk_add_f32 v[2:3], v[2:3], 1.0 op_sel_hi:[1,0]
	s_waitcnt vmcnt(3)
	v_pk_mul_f32 v[80:81], v[22:23], v[0:1]
	v_add_u32_e32 v0, 4, v4
	v_ashrrev_i32_e32 v1, 31, v0
	v_lshlrev_b64 v[0:1], 12, v[0:1]
	v_lshl_add_u64 v[94:95], s[4:5], 0, v[0:1]
	v_lshlrev_b64 v[0:1], 11, v[4:5]
	v_lshl_add_u64 v[98:99], s[72:73], 0, v[0:1]
	v_add_u32_e32 v0, 2, v4
	v_ashrrev_i32_e32 v1, 31, v0
	v_pk_mul_f32 v[78:79], v[24:25], v[2:3]
	v_lshlrev_b64 v[2:3], 11, v[0:1]
	v_lshl_add_u64 v[100:101], s[72:73], 0, v[2:3]
	v_add_u32_e32 v2, 3, v4
	v_pk_add_f32 v[6:7], v[12:13], 1.0 op_sel_hi:[1,0]
	v_pk_add_f32 v[12:13], v[16:17], 1.0 op_sel_hi:[1,0]
	v_pk_add_f32 v[16:17], v[20:21], 1.0 op_sel_hi:[1,0]
	v_add_co_u32_e32 v20, vcc, s2, v40
	v_ashrrev_i32_e32 v3, 31, v2
	v_pk_add_f32 v[10:11], v[10:11], 1.0 op_sel_hi:[1,0]
	v_pk_add_f32 v[14:15], v[14:15], 1.0 op_sel_hi:[1,0]
	v_pk_add_f32 v[18:19], v[18:19], 1.0 op_sel_hi:[1,0]
	v_addc_co_u32_e32 v21, vcc, 0, v41, vcc
	v_lshlrev_b64 v[4:5], 12, v[2:3]
	v_lshlrev_b64 v[2:3], 11, v[2:3]
	v_lshlrev_b64 v[0:1], 12, v[0:1]
	s_waitcnt vmcnt(2)
	v_pk_mul_f32 v[82:83], v[28:29], v[6:7]
	v_pk_mul_f32 v[84:85], v[26:27], v[10:11]
	s_waitcnt vmcnt(1)
	v_pk_mul_f32 v[86:87], v[32:33], v[12:13]
	v_pk_mul_f32 v[88:89], v[30:31], v[14:15]
	s_waitcnt vmcnt(0)
	v_pk_mul_f32 v[90:91], v[36:37], v[16:17]
	v_pk_mul_f32 v[92:93], v[34:35], v[18:19]
	v_lshl_add_u64 v[102:103], s[4:5], 0, v[4:5]
	v_lshl_add_u64 v[104:105], s[72:73], 0, v[2:3]
	v_lshl_add_u64 v[106:107], s[4:5], 0, v[0:1]
	global_load_dwordx4 v[0:3], v[8:9], off offset:2048 nt
	global_load_dwordx4 v[4:7], v[8:9], off offset:1024 nt
	global_load_dwordx4 v[12:15], v[8:9], off offset:3072 nt
	s_nop 0
	global_load_dwordx4 v[8:11], v[20:21], off nt
	global_load_dwordx4 v[16:19], v[40:41], off offset:3072 nt
	s_nop 0
	global_load_dwordx4 v[20:23], v[40:41], off offset:2048 nt
	global_load_dwordx4 v[24:27], v[40:41], off offset:1024 nt
	global_load_dwordx4 v[28:31], v[40:41], off nt
	s_mov_b32 s2, 0x3a800000
	s_mov_b64 s[4:5], 0x4000
	s_branch .LBB0_187

; __device__ __forceinline__ unsigned xb_add(unsigned* p, unsigned v) { return __hip_atomic_fetch_add(p, v, __ATOMIC_RELAXED, __HIP_MEMORY_SCOPE_AGENT); }
; #define GSYNC() do { for (int rs_ = 0; rs_ < REP_SYNC; ++rs_) { if (USE_CG) grid.sync(); else xcd_barrier(xbar); } } while (0)
; __device__ __forceinline__ void xcd_barrier(const XcdBarrier& b) {
;     asm volatile("s_waitcnt vmcnt(0)" ::: "memory");
;     __syncthreads();
;     if (threadIdx.x == 0) {
;         unsigned* bar = b.bar;
;         __builtin_amdgcn_s_waitcnt(0);
;         unsigned nloc = b.st[0], nx = b.st[1];
;         if (nloc == 0u) { xcd_barrier_complete(bar, b.x, nloc, nx); b.st[0] = nloc; b.st[1] = nx; }
;         const unsigned old = xb_add(&bar[XB_XSUB(b.x)], 1u);
; __global__ void __launch_bounds__(NTHR) mega_fwd(Args a) {
;     ...
;         { EpiSwiglu E; E.O = ACT; run_gemm(lds, H, 1024, (const bf16_t*)(ws + WS_W13 + f * SZ_W13), 1024, NTOK, 5632, 1024, 1 << 20, 0, E); }
;         GSYNC();
;         { EpiPlain E; E.O = Y1; E.ldc = DM; run_gemm(lds, ACT, DFF, (const bf16_t*)(ws + WS_W2 + f * SZ_W2), DFF, NTOK, 1024, DFF, 1 << 20, 0, E); }
;         GSYNC();
.LBB0_262:
	s_waitcnt vmcnt(0)
	s_barrier
	s_waitcnt vmcnt(0)
	s_barrier
	s_mov_b64 s[0:1], exec
	v_readlane_b32 s2, v249, 10
	v_readlane_b32 s3, v249, 11
	s_and_b64 s[2:3], s[0:1], s[2:3]
	s_mov_b64 exec, s[2:3]
	s_cbranch_execz .LBB0_314
	v_mov_b32_e32 v2, 0x23ffc
	ds_read_b32 v3, v2
	v_readlane_b32 s4, v251, 9
	v_readlane_b32 s5, v251, 10
	s_waitcnt lgkmcnt(0)
	v_readfirstlane_b32 s6, v3
	s_cmp_eq_u32 s6, 0
	s_cbranch_scc1 .Llbfull_314
	buffer_inv sc1
	s_add_u32 s6, s6, 0xffffcbff
	s_add_u32 s4, s4, s6
	s_addc_u32 s5, s5, -1
	v_mov_b32_e32 v2, 0x23ff8
	ds_read_b32 v3, v2
	v_mov_b32_e32 v5, 0
	v_mov_b32_e32 v6, 1
	global_atomic_add v5, v6, s[4:5]
	s_waitcnt lgkmcnt(0)
	v_add_u32_e32 v3, 1, v3
	ds_write_b32 v2, v3
	v_lshlrev_b32_e32 v3, 5, v3
.Llbspin_314:
	global_load_dword v7, v5, s[4:5] sc1
	s_waitcnt vmcnt(0)
	v_cmp_lt_u32_e32 vcc, v7, v3
	s_cbranch_vccz .Llbdone_314
	s_sleep 1
	s_branch .Llbspin_314
.Llbdone_314:
	s_waitcnt lgkmcnt(0)
	s_branch .LBB0_314
